# P3: p.ws / p.out pointers kept in SGPR pairs instead of being re-read from the LDS parameter block every scan step and attention chunk
# baseline (speedup 1.0000x reference)
.LBB0_320:
	s_and_b64 vcc, exec, s[0:1]
	s_cbranch_vccz .LBB0_463
	s_waitcnt vmcnt(0) lgkmcnt(0)
	v_bfe_u32 v0, v133, 4, 2
	s_mov_b64 s[0:1], -1
	s_cmpk_gt_i32 s2, 0x7f
	v_and_b32_e32 v129, 15, v163
	v_lshrrev_b32_e32 v135, 4, v133
	v_lshlrev_b32_e32 v158, 3, v133
	v_lshrrev_b32_e32 v101, 2, v163
	v_lshlrev_b32_e32 v128, 2, v0
	v_lshrrev_b32_e32 v154, 3, v133
	v_lshlrev_b32_e32 v157, 3, v0
	v_lshl_add_u32 v155, v0, 4, v161
	v_lshlrev_b32_e32 v156, 2, v133
	s_cbranch_scc0 .LBB0_379
	v_and_b32_e32 v0, 48, v101
	v_or_b32_e32 v107, v0, v129
	v_sub_u32_e64 v0, v0, 8 clamp
	v_min_u32_e32 v126, 32, v0
	v_add_u32_e32 v53, v126, v128
	v_sub_u32_e32 v0, v53, v107
	v_sub_u32_e64 v1, v107, 8 clamp
	v_max_i32_e32 v0, -15, v0
	v_min_u32_e32 v52, 48, v1
	v_add_u32_e32 v0, 15, v0
	v_add_u32_e32 v54, 16, v52
	v_min_u32_e32 v55, 30, v0
	v_or_b32_e32 v0, 1, v53
	v_cmp_lt_u32_e64 s[6:7], v0, v52
	v_cmp_ge_u32_e64 s[8:9], v0, v54
	v_sub_u32_e32 v0, v0, v107
	v_max_i32_e32 v0, -15, v0
	v_add_u32_e32 v0, 15, v0
	v_min_u32_e32 v56, 30, v0
	v_or_b32_e32 v0, 2, v53
	v_cmp_lt_u32_e64 s[10:11], v0, v52
	v_cmp_ge_u32_e64 s[12:13], v0, v54
	v_sub_u32_e32 v0, v0, v107
	v_max_i32_e32 v0, -15, v0
	v_add_u32_e32 v0, 15, v0
	v_min_u32_e32 v57, 30, v0
	v_or_b32_e32 v0, 3, v53
	v_cmp_lt_u32_e64 s[14:15], v0, v52
	v_cmp_ge_u32_e64 s[16:17], v0, v54
	v_sub_u32_e32 v0, v0, v107
	v_max_i32_e32 v0, -15, v0
	s_mul_i32 s0, s2, 22
	v_add_u32_e32 v0, 15, v0
	s_addk_i32 s0, 0xf500
	v_min_u32_e32 v58, 30, v0
	v_add_u32_e32 v0, 16, v53
	v_add_u32_e32 v103, s0, v162
	v_cmp_lt_u32_e64 s[18:19], v0, v52
	v_sub_u32_e32 v0, v0, v107
	v_max_i32_e32 v0, -15, v0
	v_and_b32_e32 v44, 63, v103
	v_add_u32_e32 v59, 15, v0
	v_sub_u32_e64 v0, v44, 4 clamp
	s_add_i32 s3, 0, 0x240a8
	v_min_u32_e32 v7, 56, v0
	v_mov_b32_e32 v0, s3
	ds_read_b64 v[2:3], v0
	v_lshlrev_b32_e32 v0, 3, v103
	s_movk_i32 s72, 0xf000
	v_and_or_b32 v45, v0, s72, v154
	v_lshl_or_b32 v0, v7, 6, v45
	v_ashrrev_i32_e32 v1, 31, v0
	v_and_b32_e32 v6, 0x1c0, v103
	v_lshlrev_b64 v[0:1], 10, v[0:1]
	v_and_b32_e32 v100, 56, v158
	s_waitcnt lgkmcnt(0)
	v_readfirstlane_b32 s98, v2
	v_readfirstlane_b32 s99, v3
	v_add_co_u32_e32 v4, vcc, v2, v0
	v_addc_co_u32_e32 v5, vcc, v3, v1, vcc
	v_lshlrev_b32_e32 v0, 1, v6
	v_mov_b32_e32 v1, 0
	v_add_co_u32_e32 v4, vcc, v4, v0
	v_addc_co_u32_e32 v5, vcc, v5, v1, vcc
	v_lshlrev_b32_e32 v36, 1, v100
	v_mov_b32_e32 v37, v1
	v_add_co_u32_e32 v12, vcc, v4, v36
	v_addc_co_u32_e32 v13, vcc, v5, v37, vcc
	s_mov_b32 s74, 0x8800000
	v_add_co_u32_e32 v14, vcc, s74, v12
	s_movk_i32 s73, 0xffc0
	s_nop 0
	v_addc_co_u32_e32 v15, vcc, 0, v13, vcc
	s_mov_b32 s75, 0x8808000
	v_and_or_b32 v4, v103, s73, v135
	v_add_co_u32_e32 v16, vcc, s75, v12
	v_ashrrev_i32_e32 v5, 31, v4
	s_nop 0
	v_addc_co_u32_e32 v17, vcc, 0, v13, vcc
	s_mov_b32 s76, 0x8810000
	v_lshlrev_b64 v[4:5], 13, v[4:5]
	v_add_co_u32_e32 v20, vcc, s76, v12
	v_and_b32_e32 v102, 0x78, v158
	v_lshl_add_u64 v[4:5], v[2:3], 0, v[4:5]
	v_lshlrev_b32_e32 v6, 7, v7
	v_mov_b32_e32 v7, v1
	v_addc_co_u32_e32 v21, vcc, 0, v13, vcc
	s_mov_b32 s77, 0x8818000
	v_add_co_u32_e32 v4, vcc, v4, v6
	v_addc_co_u32_e32 v5, vcc, v5, v7, vcc
	v_lshlrev_b32_e32 v38, 1, v102
	v_mov_b32_e32 v39, v1
	v_add_co_u32_e32 v22, vcc, s77, v12
	v_lshl_add_u64 v[28:29], v[4:5], 0, v[38:39]
	s_nop 0
	v_addc_co_u32_e32 v23, vcc, 0, v13, vcc
	s_mov_b32 s78, 0xa800000
	v_add_co_u32_e32 v30, vcc, s78, v28
	s_mov_b32 s79, 0xa820000
	s_nop 0
	v_addc_co_u32_e32 v31, vcc, 0, v29, vcc
	v_add_co_u32_e32 v32, vcc, s79, v28
	s_mov_b32 s80, 0xa840000
	s_nop 0
	v_addc_co_u32_e32 v33, vcc, 0, v29, vcc
	v_add_co_u32_e32 v40, vcc, s80, v28
	s_mov_b32 s81, 0xa860000
	s_nop 0
	v_addc_co_u32_e32 v41, vcc, 0, v29, vcc
	v_add_co_u32_e32 v42, vcc, s81, v28
	flat_load_dwordx4 v[4:7], v[14:15]
	flat_load_dwordx4 v[8:11], v[16:17]
	s_nop 0
	flat_load_dwordx4 v[12:15], v[20:21]
	flat_load_dwordx4 v[16:19], v[22:23]
	s_nop 0
	flat_load_dwordx4 v[20:23], v[30:31]
	flat_load_dwordx4 v[24:27], v[32:33]
	v_addc_co_u32_e32 v43, vcc, 0, v29, vcc
	flat_load_dwordx4 v[28:31], v[40:41]
	flat_load_dwordx4 v[32:35], v[42:43]
	v_lshl_or_b32 v40, v44, 6, v45
	v_ashrrev_i32_e32 v41, 31, v40
	v_lshlrev_b64 v[40:41], 10, v[40:41]
	v_add_co_u32_e32 v2, vcc, v2, v40
	v_addc_co_u32_e32 v3, vcc, v3, v41, vcc
	v_add_co_u32_e32 v2, vcc, v2, v0
	v_addc_co_u32_e32 v3, vcc, v3, v1, vcc
	v_add_co_u32_e32 v2, vcc, v2, v36
	v_addc_co_u32_e32 v3, vcc, v3, v37, vcc
	s_mov_b32 s82, 0x6800000
	v_add_co_u32_e32 v40, vcc, s82, v2
	s_mov_b32 s20, 0x6808000
	s_nop 0
	v_addc_co_u32_e32 v41, vcc, 0, v3, vcc
	v_add_co_u32_e32 v2, vcc, s20, v2
	v_mul_u32_u24_e32 v39, 0x48, v154
	s_nop 0
	v_addc_co_u32_e32 v3, vcc, 0, v3, vcc
	flat_load_dwordx4 v[44:47], v[40:41]
	flat_load_dwordx4 v[48:51], v[2:3]
	v_lshlrev_b32_e32 v39, 1, v39
	v_add3_u32 v127, v161, v39, v36
	v_mul_u32_u24_e32 v36, 0x110, v135
	v_add3_u32 v130, v161, v36, v38
	v_mbcnt_lo_u32_b32 v38, -1, 0
	v_mbcnt_hi_u32_b32 v38, -1, v38
	v_and_b32_e32 v40, 64, v38
	v_xor_b32_e32 v39, 16, v38
	v_add_u32_e32 v40, 64, v40
	v_cmp_lt_i32_e32 vcc, v39, v40
	v_add_u32_e32 v2, 17, v53
	v_add_u32_e32 v3, 18, v53
	v_add_u32_e32 v37, 19, v53
	v_cndmask_b32_e32 v39, v38, v39, vcc
	v_cmp_lt_u32_e64 s[20:21], v2, v52
	v_cmp_ge_u32_e64 s[22:23], v2, v54
	v_sub_u32_e32 v2, v2, v107
	v_cmp_lt_u32_e64 s[24:25], v3, v52
	v_cmp_ge_u32_e64 s[26:27], v3, v54
	v_sub_u32_e32 v3, v3, v107
	v_cmp_lt_u32_e64 s[28:29], v37, v52
	v_cmp_ge_u32_e64 s[30:31], v37, v54
	v_sub_u32_e32 v37, v37, v107
	v_lshlrev_b32_e32 v134, 2, v39
	v_xor_b32_e32 v39, 32, v38
	v_max_i32_e32 v2, -15, v2
	v_max_i32_e32 v3, -15, v3
	v_max_i32_e32 v37, -15, v37
	v_cmp_lt_i32_e32 vcc, v39, v40
	v_min_u32_e32 v0, 30, v59
	v_add_u32_e32 v2, 15, v2
	v_add_u32_e32 v3, 15, v3
	v_add_u32_e32 v37, 15, v37
	v_cndmask_b32_e32 v38, v38, v39, vcc
	v_min_u32_e32 v2, 30, v2
	v_min_u32_e32 v3, 30, v3
	v_min_u32_e32 v37, 30, v37
	v_sub_u32_e32 v36, v155, v157
	s_movk_i32 s83, 0x90
	v_lshlrev_b32_e32 v136, 2, v38
	v_mul_u32_u24_e32 v38, 0x88, v129
	v_lshl_add_u32 v144, v0, 2, v161
	v_add3_u32 v0, v160, v156, 0
	v_cmp_ge_u32_e64 s[0:1], v53, v52
	v_cmp_lt_u32_e64 s[36:37], v53, v52
	v_cmp_ge_u32_e64 s[4:5], v53, v54
	s_mov_b32 s39, 0
	v_mad_u32_u24 v131, v107, s83, v155
	v_or_b32_e32 v137, 64, v126
	v_mul_u32_u24_e32 v138, 0x90, v129
	v_lshl_add_u32 v139, v38, 1, v36
	v_lshl_add_u32 v140, v55, 2, v161
	v_lshl_add_u32 v141, v56, 2, v161
	v_lshl_add_u32 v142, v57, 2, v161
	v_lshl_add_u32 v143, v58, 2, v161
	v_lshl_add_u32 v145, v2, 2, v161
	v_lshl_add_u32 v146, v3, 2, v161
	v_lshl_add_u32 v148, v37, 2, v161
	v_add_u32_e32 v149, 0xb000, v0
	v_or_b32_e32 v150, 0xffffff00, v133
	s_add_i32 s84, 0, 0x24040
	s_mov_b64 s[42:43], 0x400
	s_movk_i32 s85, 0xd0
	s_mov_b64 s[44:45], 0x1c800000
	s_mov_b64 s[46:47], 0x1ca00000
	s_mov_b64 s[48:49], 0x8800000
	s_mov_b64 s[50:51], 0xa800000
	s_mov_b32 s86, 0x8000
	s_mov_b32 s87, 0x10000
	s_mov_b32 s88, 0xf149f2ca
	s_mov_b32 s89, 0xefa18f08
	v_lshlrev_b32_e32 v104, 1, v128
	s_mov_b64 s[52:53], 0x6800000
	v_mov_b32_e32 v151, 0xf149f2ca
	s_mov_b32 s90, 0
	s_branch .LBB0_324

.LBB0_330:
	s_cmp_eq_u32 s91, 5
	s_mov_b64 s[56:57], -1
	s_waitcnt lgkmcnt(0)
	s_barrier
	s_cbranch_scc1 .LBB0_336
	v_mov_b32_e32 v0, s3
	v_mov_b32_e32 v68, s98
	v_mov_b32_e32 v69, s99
	s_lshl_b32 s58, s91, 7
	s_cmp_gt_u32 s91, 2
	s_cbranch_scc0 .LBB0_333
	s_add_i32 s38, s58, 0xfffffe80
	v_add_u32_e32 v2, s38, v153
	v_ashrrev_i32_e32 v3, 31, v2
	v_lshlrev_b64 v[2:3], 10, v[2:3]
	s_waitcnt lgkmcnt(0)
	v_add_co_u32_e32 v2, vcc, v68, v2
	v_addc_co_u32_e32 v3, vcc, v69, v3, vcc
	v_add_co_u32_e32 v70, vcc, v68, v108
	v_addc_co_u32_e32 v71, vcc, v69, v109, vcc
	v_lshl_add_u64 v[2:3], v[2:3], 0, s[44:45]
	v_lshl_add_u64 v[70:71], v[70:71], 0, s[46:47]
	s_mov_b64 s[56:57], 0

.LBB0_336:
	s_and_b64 vcc, exec, s[56:57]
	s_cbranch_vccz .LBB0_367
	s_andn2_b64 vcc, exec, s[54:55]
	s_cbranch_vccnz .LBB0_339
	v_mov_b32_e32 v0, s3
	v_mov_b32_e32 v2, s98
	v_mov_b32_e32 v3, s99
	v_mov_b32_e32 v123, v1
	v_lshlrev_b32_e32 v0, 1, v100
	v_mov_b32_e32 v125, v1
	s_waitcnt lgkmcnt(0)
	v_add_co_u32_e32 v4, vcc, v2, v112
	v_addc_co_u32_e32 v5, vcc, v3, v113, vcc
	v_add_co_u32_e32 v6, vcc, v2, v114
	v_addc_co_u32_e32 v7, vcc, v3, v115, vcc
	v_add_co_u32_e32 v4, vcc, v4, v122
	v_addc_co_u32_e32 v5, vcc, v5, v123, vcc
	v_add_co_u32_e32 v12, vcc, v4, v0
	v_addc_co_u32_e32 v13, vcc, v5, v1, vcc
	v_add_co_u32_e32 v4, vcc, v6, v124
	v_addc_co_u32_e32 v5, vcc, v7, v125, vcc
	v_lshlrev_b32_e32 v6, 1, v102
	v_mov_b32_e32 v7, v1
	v_add_co_u32_e32 v28, vcc, v4, v6
	v_addc_co_u32_e32 v29, vcc, v5, v7, vcc
	v_add_co_u32_e32 v4, vcc, s74, v12
	v_lshl_add_u64 v[2:3], v[2:3], 0, v[116:117]
	s_nop 0
	v_addc_co_u32_e32 v5, vcc, 0, v13, vcc
	v_add_co_u32_e32 v8, vcc, s75, v12
	v_lshl_add_u64 v[2:3], v[2:3], 0, v[122:123]
	s_nop 0
	v_addc_co_u32_e32 v9, vcc, 0, v13, vcc
	v_add_co_u32_e32 v14, vcc, s76, v12
	v_lshl_add_u64 v[2:3], v[2:3], 0, v[0:1]
	s_nop 0
	v_addc_co_u32_e32 v15, vcc, 0, v13, vcc
	v_add_co_u32_e32 v16, vcc, s77, v12
	global_load_dwordx4 v[4:7], v[4:5], off
	s_nop 0
	global_load_dwordx4 v[8:11], v[8:9], off
	v_addc_co_u32_e32 v17, vcc, 0, v13, vcc
	v_add_co_u32_e32 v20, vcc, s78, v28
	global_load_dwordx4 v[12:15], v[14:15], off
	s_nop 0
	global_load_dwordx4 v[16:19], v[16:17], off
	v_addc_co_u32_e32 v21, vcc, 0, v29, vcc
	v_add_co_u32_e32 v24, vcc, s79, v28
	s_nop 1
	v_addc_co_u32_e32 v25, vcc, 0, v29, vcc
	v_add_co_u32_e32 v30, vcc, s80, v28
	global_load_dwordx4 v[20:23], v[20:21], off
	s_nop 0
	global_load_dwordx4 v[24:27], v[24:25], off
	v_addc_co_u32_e32 v31, vcc, 0, v29, vcc
	v_add_co_u32_e32 v32, vcc, s81, v28
	s_nop 1
	v_addc_co_u32_e32 v33, vcc, 0, v29, vcc
	v_add_co_u32_e32 v44, vcc, 0x6800000, v2
	global_load_dwordx4 v[28:31], v[30:31], off
	s_nop 0
	global_load_dwordx4 v[32:35], v[32:33], off
	v_addc_co_u32_e32 v45, vcc, 0, v3, vcc
	v_add_co_u32_e32 v2, vcc, 0x6808000, v2
	s_nop 1
	v_addc_co_u32_e32 v3, vcc, 0, v3, vcc
	global_load_dwordx4 v[44:47], v[44:45], off
	s_nop 0
	global_load_dwordx4 v[48:51], v[2:3], off

.LBB0_379:
	s_and_b64 vcc, exec, s[0:1]
	s_cbranch_vccz .LBB0_463
	v_bfe_u32 v100, v147, 2, 1
	v_mov_b32_e32 v226, 0x240a0
	v_mov_b32_e32 v227, 0x240a8
	ds_read_b64 v[228:229], v226
	ds_read_b64 v[230:231], v227
	s_waitcnt lgkmcnt(0)
	v_readfirstlane_b32 s100, v228
	v_readfirstlane_b32 s101, v229
	v_readfirstlane_b32 s98, v230
	v_readfirstlane_b32 s99, v231
	v_and_b32_e32 v221, 1, v147
	v_mov_b32_e32 v219, 0
	v_mov_b32_e32 v223, 0
	s_nop 0
	v_mul_u32_u24_e32 v220, 0x4400, v221
	v_lshlrev_b32_e32 v218, 15, v221
	v_lshlrev_b32_e32 v222, 19, v221
	v_mul_u32_u24_e32 v221, 0x12000, v221
	s_add_i32 s0, 0, 0x24048
	s_add_i32 s1, 0, 0x24050
	v_mov_b32_e32 v0, s1
	v_mov_b32_e32 v1, s0
	v_cmp_eq_u32_e64 s[0:1], 0, v100
	v_bfe_u32 v2, v147, 3, 2
	v_mov_b32_e32 v137, 0
	v_cndmask_b32_e64 v0, v0, v1, s[0:1]
	ds_read_b64 v[0:1], v0
	v_lshlrev_b32_e32 v2, 2, v2
	v_mov_b32_e32 v3, v137
	s_add_i32 s12, 0, 0x240a8
	v_ashrrev_i32_e32 v5, 3, v147
	s_waitcnt lgkmcnt(0)
	v_add_co_u32_e32 v0, vcc, v0, v2
	v_addc_co_u32_e32 v1, vcc, v1, v3, vcc
	global_load_dword v44, v[0:1], off
	v_and_b32_e32 v1, 4, v147
	v_lshrrev_b32_e32 v0, 3, v147
	v_cmp_ne_u32_e64 s[6:7], 0, v1
	v_mov_b32_e32 v1, s12
	v_bfi_b32 v96, -4, v5, v0
	ds_read_b64 v[0:1], v1
	v_mov_b32_e32 v2, 0x1ce00000
	v_mov_b32_e32 v3, 0x1cc00000
	v_lshlrev_b32_e32 v4, 6, v147
	v_and_b32_e32 v106, 0xc0, v4
	v_cndmask_b32_e64 v136, v2, v3, s[0:1]
	v_lshlrev_b32_e32 v2, 8, v96
	v_lshl_or_b32 v102, v96, 7, v135
	v_or3_b32 v104, v2, v106, v135
	v_ashrrev_i32_e32 v103, 31, v102
	v_ashrrev_i32_e32 v105, 31, v104
	v_lshlrev_b64 v[2:3], 9, v[102:103]
	v_lshlrev_b64 v[4:5], 9, v[104:105]
	s_waitcnt lgkmcnt(0)
	v_add_co_u32_e32 v6, vcc, v0, v136
	v_addc_co_u32_e32 v7, vcc, v1, v137, vcc
	v_and_b32_e32 v134, 0x78, v158
	s_mov_b64 s[4:5], 0x1d000000
	v_lshlrev_b32_e32 v136, 8, v100
	v_add_co_u32_e32 v0, vcc, v0, v4
	v_addc_co_u32_e32 v1, vcc, v1, v5, vcc
	v_add_co_u32_e32 v28, vcc, v6, v2
	v_addc_co_u32_e32 v29, vcc, v7, v3, vcc
	v_lshlrev_b32_e32 v98, 1, v134
	v_mov_b32_e32 v99, v137
	v_lshl_add_u64 v[30:31], v[0:1], 0, s[4:5]
	v_add_co_u32_e32 v0, vcc, v28, v136
	v_addc_co_u32_e32 v1, vcc, v29, v137, vcc
	s_movk_i32 s9, 0x2000
	v_add_co_u32_e32 v32, vcc, v0, v98
	v_addc_co_u32_e32 v33, vcc, v1, v99, vcc
	v_add_co_u32_e32 v32, vcc, v32, v218
	v_addc_co_u32_e32 v33, vcc, v33, v219, vcc
	v_add_co_u32_e32 v12, vcc, s9, v32
	s_movk_i32 s10, 0x4000
	s_nop 0
	v_addc_co_u32_e32 v13, vcc, 0, v33, vcc
	v_add_co_u32_e32 v14, vcc, s10, v32
	s_movk_i32 s11, 0x6000
	s_nop 0
	v_addc_co_u32_e32 v15, vcc, 0, v33, vcc
	v_add_co_u32_e32 v34, vcc, s11, v32
	s_mov_b32 s13, 0x8000
	s_nop 0
	v_addc_co_u32_e32 v35, vcc, 0, v33, vcc
	v_add_co_u32_e32 v36, vcc, s13, v32
	s_mov_b32 s14, 0xa000
	s_nop 0
	v_addc_co_u32_e32 v37, vcc, 0, v33, vcc
	v_add_co_u32_e32 v38, vcc, s14, v32
	s_mov_b32 s15, 0xc000
	s_nop 0
	v_addc_co_u32_e32 v39, vcc, 0, v33, vcc
	v_add_co_u32_e32 v42, vcc, s15, v32
	s_mov_b32 s16, 0xe000
	v_lshl_add_u64 v[2:3], v[30:31], 0, v[136:137]
	v_addc_co_u32_e32 v43, vcc, 0, v33, vcc
	v_add_co_u32_e32 v40, vcc, v2, v98
	v_addc_co_u32_e32 v41, vcc, v3, v99, vcc
	global_load_dwordx4 v[0:3], v[12:13], off
	global_load_dwordx4 v[4:7], v[14:15], off
	global_load_dwordx4 v[8:11], v[34:35], off
	v_add_co_u32_e32 v42, vcc, s16, v32
	s_mov_b32 s8, 0x3fb8aa3b
	s_nop 0
	v_addc_co_u32_e32 v43, vcc, 0, v33, vcc
	v_add_co_u32_e32 v48, vcc, s9, v40
	v_xor_b32_e32 v136, 0x100, v136
	s_nop 0
	v_addc_co_u32_e32 v49, vcc, 0, v41, vcc
	v_add_co_u32_e32 v28, vcc, v28, v136
	v_addc_co_u32_e32 v29, vcc, v29, v137, vcc
	v_add_co_u32_e32 v76, vcc, v28, v98
	v_addc_co_u32_e32 v77, vcc, v29, v99, vcc
	v_add_co_u32_e32 v76, vcc, v76, v218
	v_addc_co_u32_e32 v77, vcc, v77, v219, vcc
	v_add_co_u32_e32 v28, vcc, v30, v136
	v_addc_co_u32_e32 v29, vcc, v31, v137, vcc
	v_add_co_u32_e32 v88, vcc, v28, v98
	v_addc_co_u32_e32 v89, vcc, v29, v99, vcc
	v_mov_b32_e32 v97, 0x12800000
	s_mov_b32 s4, 0xc2ce8ed0
	s_waitcnt vmcnt(0)
	v_mul_f32_e32 v107, 0x43000000, v44
	v_mul_f32_e32 v108, 0x3fb8aa3b, v107
	v_fma_f32 v12, v107, s8, -v108
	v_fmamk_f32 v110, v107, 0x32a5705f, v12
	global_load_dwordx4 v[12:15], v[32:33], off
	global_load_dwordx4 v[36:39], v[40:41], off
	s_nop 0
	global_load_dwordx4 v[44:47], v[48:49], off
	v_add_co_u32_e32 v42, vcc, s10, v40
	v_rndne_f32_e32 v109, v108
	s_nop 0
	v_addc_co_u32_e32 v43, vcc, 0, v41, vcc
	v_add_co_u32_e32 v40, vcc, s11, v40
	v_sub_f32_e32 v99, v108, v109
	s_nop 0
	v_addc_co_u32_e32 v41, vcc, 0, v41, vcc
	v_add_co_u32_e32 v48, vcc, s9, v76
	global_load_dwordx4 v[60:63], v[42:43], off
	global_load_dwordx4 v[64:67], v[40:41], off
	v_addc_co_u32_e32 v49, vcc, 0, v77, vcc
	v_add_co_u32_e32 v50, vcc, s10, v76
	v_add_f32_e32 v99, v99, v110
	s_nop 0
	v_addc_co_u32_e32 v51, vcc, 0, v77, vcc
	v_add_co_u32_e32 v52, vcc, s11, v76
	global_load_dwordx4 v[28:31], v[48:49], off
	global_load_dwordx4 v[40:43], v[50:51], off
	v_addc_co_u32_e32 v53, vcc, 0, v77, vcc
	v_add_co_u32_e32 v54, vcc, s13, v76
	v_exp_f32_e32 v99, v99
	s_nop 0
	v_addc_co_u32_e32 v55, vcc, 0, v77, vcc
	global_load_dwordx4 v[48:51], v[52:53], off
	v_add_co_u32_e32 v52, vcc, s14, v76
	v_cvt_i32_f32_e32 v108, v109
	s_nop 0
	v_addc_co_u32_e32 v53, vcc, 0, v77, vcc
	v_add_co_u32_e32 v54, vcc, s15, v76
	v_mov_b32_e32 v109, 0x10800000
	s_nop 0
	v_addc_co_u32_e32 v55, vcc, 0, v77, vcc
	v_add_co_u32_e32 v90, vcc, s16, v76
	v_addc_co_u32_e32 v91, vcc, 0, v77, vcc
	v_add_co_u32_e32 v92, vcc, s9, v88
	global_load_dwordx4 v[52:55], v[76:77], off
	global_load_dwordx4 v[80:83], v[88:89], off
	v_addc_co_u32_e32 v93, vcc, 0, v89, vcc
	global_load_dwordx4 v[84:87], v[92:93], off
	v_add_co_u32_e32 v90, vcc, s10, v88
	v_cndmask_b32_e64 v138, v97, v109, s[0:1]
	s_nop 0
	v_addc_co_u32_e32 v91, vcc, 0, v89, vcc
	v_add_co_u32_e32 v92, vcc, s11, v88
	v_ldexp_f32 v97, v99, v108
	s_nop 0
	v_addc_co_u32_e32 v93, vcc, 0, v89, vcc
	global_load_dwordx4 v[88:91], v[90:91], off
	s_nop 0
	global_load_dwordx4 v[92:95], v[92:93], off
	v_cmp_ngt_f32_e32 vcc, s4, v107
	s_mov_b32 s4, 0x42b17218
	v_mov_b32_e32 v99, 0x7f800000
	v_cndmask_b32_e32 v97, 0, v97, vcc
	v_cmp_nlt_f32_e32 vcc, s4, v107
	v_and_b32_e32 v165, 48, v101
	v_or_b32_e32 v163, v165, v129
	v_cndmask_b32_e32 v140, v99, v97, vcc
	v_mul_u32_u24_e32 v97, 0x88, v135
	v_lshlrev_b32_e32 v97, 1, v97
	v_add3_u32 v159, v161, v97, v98
	v_or_b32_e32 v98, v106, v163
	s_movk_i32 s4, 0x110
	v_mul_u32_u24_e32 v164, 0x88, v129
	v_ashrrev_i32_e32 v97, 31, v96
	v_lshlrev_b32_e32 v98, 7, v98
	s_mov_b32 s3, 0
	v_mov_b32_e32 v139, v137
	v_mov_b32_e32 v141, v140
	v_mov_b32_e32 v142, v140
	v_mov_b32_e32 v143, v140
	v_mad_u32_u24 v166, v163, s4, v155
	v_lshl_add_u32 v167, v164, 1, v155
	v_sub_u32_e32 v216, v159, v221
	v_sub_u32_e32 v217, v167, v221
	v_add_u32_e32 v216, v216, v220
	v_add_u32_e32 v224, 0x12000, v216
	v_add_u32_e32 v225, 0x12000, v217
	v_lshlrev_b64 v[144:145], 13, v[102:103]
	v_lshlrev_b64 v[146:147], 13, v[104:105]
	v_lshlrev_b64 v[148:149], 22, v[96:97]
	v_lshlrev_b32_e32 v150, 16, v100
	v_mov_b32_e32 v151, v137
	s_mov_b32 s13, 30
	s_add_i32 s14, 0, 0x240a0
	v_lshlrev_b32_e32 v152, 1, v98
	s_mov_b32 s15, 0x20000
	s_mov_b32 s16, 0x40000
	s_mov_b32 s17, 0x60000
	s_mov_b32 s18, 0x80000
	s_mov_b32 s19, 0xa0000
	s_mov_b32 s20, 0xc0000
	s_mov_b32 s21, 0xe0000
	s_mov_b32 s22, 0x14800000
	s_mov_b32 s23, 0
	v_mov_b32_e32 v124, v137
	v_mov_b32_e32 v125, v137
	v_mov_b32_e32 v126, v137
	v_mov_b32_e32 v127, v137
	v_mov_b32_e32 v120, v137
	v_mov_b32_e32 v121, v137
	v_mov_b32_e32 v122, v137
	v_mov_b32_e32 v123, v137
	v_mov_b32_e32 v112, v137
	v_mov_b32_e32 v113, v137
	v_mov_b32_e32 v114, v137
	v_mov_b32_e32 v115, v137
	v_mov_b32_e32 v108, v137
	v_mov_b32_e32 v109, v137
	v_mov_b32_e32 v110, v137
	v_mov_b32_e32 v111, v137
	v_mov_b32_e32 v104, v137
	v_mov_b32_e32 v105, v137
	v_mov_b32_e32 v106, v137
	v_mov_b32_e32 v107, v137
	v_mov_b32_e32 v100, v137
	v_mov_b32_e32 v101, v137
	v_mov_b32_e32 v102, v137
	v_mov_b32_e32 v103, v137
	v_mov_b32_e32 v96, v137
	v_mov_b32_e32 v97, v137
	v_mov_b32_e32 v98, v137
	v_mov_b32_e32 v99, v137
	v_mov_b32_e32 v116, v137
	v_mov_b32_e32 v117, v137
	v_mov_b32_e32 v118, v137
	v_mov_b32_e32 v119, v137
	s_branch .LBB0_382

.LBB0_389:
	v_cndmask_b32_e64 v130, 0, 1, s[8:9]
	v_cmp_ne_u32_e64 s[4:5], 1, v130
	s_andn2_b64 vcc, exec, s[8:9]
	v_lshlrev_b32_e32 v130, 1, v128
	s_cbranch_vccnz .LBB0_391
	v_mov_b32_e32 v131, s14
	v_mov_b32_e32 v168, s100
	v_mov_b32_e32 v169, s101
	v_lshlrev_b64 v[170:171], 17, v[136:137]
	v_mov_b32_e32 v153, v137
	v_mov_b32_e32 v131, v137
	s_waitcnt lgkmcnt(0)
	v_lshl_add_u64 v[168:169], v[168:169], 0, v[170:171]
	v_lshl_add_u64 v[168:169], v[168:169], 0, v[148:149]
	v_lshl_add_u64 v[168:169], v[168:169], 0, v[150:151]
	v_lshl_add_u64 v[168:169], v[168:169], 0, v[152:153]
	v_and_b32_e32 v170, 4, v128
	v_lshlrev_b32_e32 v170, 3, v170
	v_and_b32_e32 v171, 8, v128
	v_lshl_add_u32 v170, v171, 1, v170
	v_mov_b32_e32 v171, 0
	v_lshl_add_u64 v[168:169], v[168:169], 0, v[170:171]
	v_cvt_pk_bf16_f32 v240, v124, v125
	v_cvt_pk_bf16_f32 v241, v126, v127
	v_cvt_pk_bf16_f32 v242, v120, v121
	v_cvt_pk_bf16_f32 v243, v122, v123
	s_nop 1
	v_permlane16_swap_b32_e32 v240, v242
	v_permlane16_swap_b32_e32 v241, v243
	global_store_dwordx4 v[168:169], v[240:243], off
	v_cvt_pk_bf16_f32 v244, v112, v113
	v_cvt_pk_bf16_f32 v245, v114, v115
	v_cvt_pk_bf16_f32 v246, v108, v109
	v_cvt_pk_bf16_f32 v247, v110, v111
	s_nop 1
	v_permlane16_swap_b32_e32 v244, v246
	v_permlane16_swap_b32_e32 v245, v247
	global_store_dwordx4 v[168:169], v[244:247], off offset:64
	v_cvt_pk_bf16_f32 v248, v104, v105
	v_cvt_pk_bf16_f32 v249, v106, v107
	v_cvt_pk_bf16_f32 v250, v100, v101
	v_cvt_pk_bf16_f32 v251, v102, v103
	s_nop 1
	v_permlane16_swap_b32_e32 v248, v250
	v_permlane16_swap_b32_e32 v249, v251
	global_store_dwordx4 v[168:169], v[248:251], off offset:128
	v_cvt_pk_bf16_f32 v252, v96, v97
	v_cvt_pk_bf16_f32 v253, v98, v99
	v_cvt_pk_bf16_f32 v254, v116, v117
	v_cvt_pk_bf16_f32 v255, v118, v119
	s_nop 1
	v_permlane16_swap_b32_e32 v252, v254
	v_permlane16_swap_b32_e32 v253, v255
	global_store_dwordx4 v[168:169], v[252:255], off offset:192
.LBB0_391:
	s_cmp_lg_u32 s3, 32
	s_cselect_b64 s[10:11], -1, 0
	s_cmp_eq_u32 s3, 32
	ds_write_b128 v216, v[12:15]
	ds_write_b128 v216, v[0:3] offset:4352
	ds_write_b128 v216, v[4:7] offset:8704
	ds_write_b128 v216, v[8:11] offset:13056
	ds_write_b128 v159, v[36:39] offset:34816
	ds_write_b128 v159, v[44:47] offset:39168
	ds_write_b128 v159, v[60:63] offset:43520
	ds_write_b128 v159, v[64:67] offset:47872
	s_cbranch_scc1 .LBB0_393
	v_mov_b32_e32 v0, s12
	v_mov_b32_e32 v0, s98
	v_mov_b32_e32 v1, s99
	s_add_i32 s25, s13, 1
	v_mov_b32_e32 v2, s3
	v_mov_b32_e32 v3, s25
	v_cndmask_b32_e64 v4, v3, v2, s[0:1]
	s_waitcnt lgkmcnt(0)
	v_add_co_u32_e32 v2, vcc, v0, v138
	v_addc_co_u32_e32 v3, vcc, v1, v139, vcc
	v_add_co_u32_e32 v2, vcc, v2, v144
	v_addc_co_u32_e32 v3, vcc, v3, v145, vcc
	v_lshlrev_b32_e32 v136, 8, v4
	v_add_co_u32_e32 v2, vcc, v2, v136
	v_addc_co_u32_e32 v3, vcc, v3, v137, vcc
	v_lshlrev_b32_e32 v4, 1, v134
	v_mov_b32_e32 v5, v137
	v_add_co_u32_e32 v0, vcc, v0, v146
	v_addc_co_u32_e32 v1, vcc, v1, v147, vcc
	v_add_co_u32_e32 v24, vcc, v2, v4
	v_addc_co_u32_e32 v25, vcc, v3, v5, vcc
	v_add_co_u32_e32 v24, vcc, v24, v222
	v_addc_co_u32_e32 v25, vcc, v25, v223, vcc
	v_add_co_u32_e32 v0, vcc, v0, v136
	v_addc_co_u32_e32 v1, vcc, v1, v137, vcc
	v_add_co_u32_e32 v60, vcc, v0, v4
	v_addc_co_u32_e32 v61, vcc, v1, v5, vcc
	v_add_co_u32_e32 v0, vcc, s15, v24
	s_nop 1
	v_addc_co_u32_e32 v1, vcc, 0, v25, vcc
	v_add_co_u32_e32 v4, vcc, s16, v24
	global_load_dwordx4 v[12:15], v[24:25], off
	s_nop 0
	global_load_dwordx4 v[0:3], v[0:1], off
	v_addc_co_u32_e32 v5, vcc, 0, v25, vcc
	v_add_co_u32_e32 v8, vcc, s17, v24
	s_nop 1
	v_addc_co_u32_e32 v9, vcc, 0, v25, vcc
	v_add_co_u32_e32 v16, vcc, s18, v24
	global_load_dwordx4 v[4:7], v[4:5], off
	s_nop 0
	global_load_dwordx4 v[8:11], v[8:9], off
	v_addc_co_u32_e32 v17, vcc, 0, v25, vcc
	v_add_co_u32_e32 v20, vcc, s19, v24
	s_nop 1
	v_addc_co_u32_e32 v21, vcc, 0, v25, vcc
	v_add_co_u32_e32 v26, vcc, s20, v24
	s_nop 0
	v_addc_co_u32_e32 v27, vcc, 0, v25, vcc
	v_add_co_u32_e32 v32, vcc, s21, v24
	s_nop 1
	v_addc_co_u32_e32 v33, vcc, 0, v25, vcc
	v_add_co_u32_e32 v36, vcc, s22, v60
	s_nop 0
	v_addc_co_u32_e32 v37, vcc, 0, v61, vcc
	v_add_co_u32_e32 v44, vcc, 0x14820000, v60
	s_nop 1
	v_addc_co_u32_e32 v45, vcc, 0, v61, vcc
	v_add_co_u32_e32 v62, vcc, 0x14840000, v60
	global_load_dwordx4 v[36:39], v[36:37], off
	s_nop 0
	global_load_dwordx4 v[44:47], v[44:45], off
	v_addc_co_u32_e32 v63, vcc, 0, v61, vcc
	v_add_co_u32_e32 v64, vcc, 0x14860000, v60
	s_nop 1
	v_addc_co_u32_e32 v65, vcc, 0, v61, vcc
	global_load_dwordx4 v[60:63], v[62:63], off
	s_nop 0
	global_load_dwordx4 v[64:67], v[64:65], off

.LBB0_400:
	s_and_b64 vcc, exec, s[4:5]
	s_cbranch_vccnz .LBB0_402
	v_mov_b32_e32 v131, s14
	v_mov_b32_e32 v168, s100
	v_mov_b32_e32 v169, s101
	v_lshlrev_b64 v[170:171], 17, v[136:137]
	v_mov_b32_e32 v153, v137
	v_mov_b32_e32 v131, v137
	s_waitcnt lgkmcnt(0)
	v_add_co_u32_e32 v168, vcc, v168, v170
	v_addc_co_u32_e32 v169, vcc, v169, v171, vcc
	v_add_co_u32_e32 v168, vcc, v168, v148
	v_addc_co_u32_e32 v169, vcc, v169, v149, vcc
	v_add_co_u32_e32 v168, vcc, v168, v150
	v_addc_co_u32_e32 v169, vcc, v169, v151, vcc
	v_add_co_u32_e32 v168, vcc, v168, v152
	v_addc_co_u32_e32 v169, vcc, v169, v153, vcc
	v_and_b32_e32 v170, 4, v128
	v_lshlrev_b32_e32 v170, 3, v170
	v_and_b32_e32 v171, 8, v128
	v_lshl_add_u32 v170, v171, 1, v170
	v_mov_b32_e32 v171, 0
	v_add_co_u32_e32 v168, vcc, v168, v170
	v_addc_co_u32_e32 v169, vcc, v169, v171, vcc
	v_cvt_pk_bf16_f32 v240, v124, v125
	v_cvt_pk_bf16_f32 v241, v126, v127
	v_cvt_pk_bf16_f32 v242, v120, v121
	v_cvt_pk_bf16_f32 v243, v122, v123
	s_nop 1
	v_permlane16_swap_b32_e32 v240, v242
	v_permlane16_swap_b32_e32 v241, v243
	global_store_dwordx4 v[168:169], v[240:243], off
	v_cvt_pk_bf16_f32 v244, v116, v117
	v_cvt_pk_bf16_f32 v245, v118, v119
	v_cvt_pk_bf16_f32 v246, v112, v113
	v_cvt_pk_bf16_f32 v247, v114, v115
	s_nop 1
	v_permlane16_swap_b32_e32 v244, v246
	v_permlane16_swap_b32_e32 v245, v247
	global_store_dwordx4 v[168:169], v[244:247], off offset:64
	v_cvt_pk_bf16_f32 v248, v108, v109
	v_cvt_pk_bf16_f32 v249, v110, v111
	v_cvt_pk_bf16_f32 v250, v104, v105
	v_cvt_pk_bf16_f32 v251, v106, v107
	s_nop 1
	v_permlane16_swap_b32_e32 v248, v250
	v_permlane16_swap_b32_e32 v249, v251
	global_store_dwordx4 v[168:169], v[248:251], off offset:128
	v_cvt_pk_bf16_f32 v252, v100, v101
	v_cvt_pk_bf16_f32 v253, v102, v103
	v_cvt_pk_bf16_f32 v254, v96, v97
	v_cvt_pk_bf16_f32 v255, v98, v99
	s_nop 1
	v_permlane16_swap_b32_e32 v252, v254
	v_permlane16_swap_b32_e32 v253, v255
	global_store_dwordx4 v[168:169], v[252:255], off offset:192
.LBB0_402:
	s_andn2_b64 vcc, exec, s[10:11]
	ds_write_b128 v224, v[52:55]
	ds_write_b128 v224, v[28:31] offset:4352
	ds_write_b128 v224, v[40:43] offset:8704
	ds_write_b128 v224, v[48:51] offset:13056
	ds_write_b128 v159, v[80:83] offset:52224
	ds_write_b128 v159, v[84:87] offset:56576
	ds_write_b128 v159, v[88:91] offset:60928
	ds_write_b128 v159, v[92:95] offset:65280
	s_cbranch_vccnz .LBB0_381
	v_mov_b32_e32 v28, s12
	v_mov_b32_e32 v28, s98
	v_mov_b32_e32 v29, s99
	v_mov_b32_e32 v30, s13
	v_mov_b32_e32 v31, s8
	v_cndmask_b32_e64 v30, v30, v31, s[0:1]
	v_lshlrev_b32_e32 v136, 8, v30
	s_waitcnt lgkmcnt(0)
	v_add_co_u32_e32 v30, vcc, v28, v138
	v_addc_co_u32_e32 v31, vcc, v29, v139, vcc
	v_add_co_u32_e32 v30, vcc, v30, v144
	v_addc_co_u32_e32 v31, vcc, v31, v145, vcc
	v_add_co_u32_e32 v30, vcc, v30, v136
	v_addc_co_u32_e32 v31, vcc, v31, v137, vcc
	v_lshlrev_b32_e32 v40, 1, v134
	v_mov_b32_e32 v41, v137
	v_add_co_u32_e32 v28, vcc, v28, v146
	v_addc_co_u32_e32 v29, vcc, v29, v147, vcc
	v_add_co_u32_e32 v72, vcc, v30, v40
	v_addc_co_u32_e32 v73, vcc, v31, v41, vcc
	v_add_co_u32_e32 v72, vcc, v72, v222
	v_addc_co_u32_e32 v73, vcc, v73, v223, vcc
	v_add_co_u32_e32 v28, vcc, v28, v136
	v_addc_co_u32_e32 v29, vcc, v29, v137, vcc
	v_add_co_u32_e32 v88, vcc, v28, v40
	v_addc_co_u32_e32 v89, vcc, v29, v41, vcc
	v_add_co_u32_e32 v28, vcc, s15, v72
	s_nop 1
	v_addc_co_u32_e32 v29, vcc, 0, v73, vcc
	v_add_co_u32_e32 v40, vcc, s16, v72
	global_load_dwordx4 v[52:55], v[72:73], off
	s_nop 0
	global_load_dwordx4 v[28:31], v[28:29], off
	v_addc_co_u32_e32 v41, vcc, 0, v73, vcc
	v_add_co_u32_e32 v48, vcc, s17, v72
	s_nop 1
	v_addc_co_u32_e32 v49, vcc, 0, v73, vcc
	v_add_co_u32_e32 v56, vcc, s18, v72
	global_load_dwordx4 v[40:43], v[40:41], off
	s_nop 0
	global_load_dwordx4 v[48:51], v[48:49], off
	v_addc_co_u32_e32 v57, vcc, 0, v73, vcc
	v_add_co_u32_e32 v68, vcc, s19, v72
	s_nop 1
	v_addc_co_u32_e32 v69, vcc, 0, v73, vcc
	v_add_co_u32_e32 v74, vcc, s20, v72
	s_nop 0
	v_addc_co_u32_e32 v75, vcc, 0, v73, vcc
	v_add_co_u32_e32 v76, vcc, s21, v72
	s_nop 1
	v_addc_co_u32_e32 v77, vcc, 0, v73, vcc
	v_add_co_u32_e32 v80, vcc, s22, v88
	s_nop 0
	v_addc_co_u32_e32 v81, vcc, 0, v89, vcc
	v_add_co_u32_e32 v84, vcc, 0x14820000, v88
	s_nop 1
	v_addc_co_u32_e32 v85, vcc, 0, v89, vcc
	v_add_co_u32_e32 v90, vcc, 0x14840000, v88
	global_load_dwordx4 v[80:83], v[80:81], off
	s_nop 0
	global_load_dwordx4 v[84:87], v[84:85], off
	v_addc_co_u32_e32 v91, vcc, 0, v89, vcc
	v_add_co_u32_e32 v92, vcc, 0x14860000, v88
	s_nop 1
	v_addc_co_u32_e32 v93, vcc, 0, v89, vcc
	global_load_dwordx4 v[88:91], v[90:91], off
	s_nop 0
	global_load_dwordx4 v[92:95], v[92:93], off
	s_branch .LBB0_381

.LBB0_406:
	s_waitcnt vmcnt(0)
	v_sub_u32_e64 v0, v163, 8 clamp
	v_min_u32_e32 v42, 48, v0
	v_sub_u32_e64 v0, v165, 8 clamp
	v_min_u32_e32 v105, 32, v0
	v_add_u32_e32 v43, v105, v128
	v_sub_u32_e32 v0, v43, v163
	v_max_i32_e32 v0, -15, v0
	v_add_u32_e32 v0, 15, v0
	v_add_u32_e32 v52, 16, v42
	v_min_u32_e32 v53, 30, v0
	v_or_b32_e32 v0, 1, v43
	v_cmp_lt_u32_e64 s[6:7], v0, v42
	v_cmp_ge_u32_e64 s[8:9], v0, v52
	v_sub_u32_e32 v0, v0, v163
	v_max_i32_e32 v0, -15, v0
	v_add_u32_e32 v0, 15, v0
	v_min_u32_e32 v54, 30, v0
	v_or_b32_e32 v0, 2, v43
	v_cmp_lt_u32_e64 s[10:11], v0, v42
	v_cmp_ge_u32_e64 s[12:13], v0, v52
	v_sub_u32_e32 v0, v0, v163
	v_max_i32_e32 v0, -15, v0
	v_add_u32_e32 v0, 15, v0
	v_min_u32_e32 v55, 30, v0
	v_or_b32_e32 v0, 3, v43
	s_mul_i32 s0, s2, 10
	v_cmp_lt_u32_e64 s[14:15], v0, v42
	v_cmp_ge_u32_e64 s[16:17], v0, v52
	v_sub_u32_e32 v0, v0, v163
	s_addk_i32 s0, 0xb00
	v_max_i32_e32 v0, -15, v0
	v_add_u32_e32 v101, s0, v162
	v_add_u32_e32 v0, 15, v0
	v_min_u32_e32 v56, 30, v0
	v_add_u32_e32 v0, 16, v43
	v_and_b32_e32 v44, 63, v101
	v_cmp_lt_u32_e64 s[18:19], v0, v42
	v_sub_u32_e32 v57, v0, v163
	v_sub_u32_e64 v0, v44, 4 clamp
	s_add_i32 s3, 0, 0x240a8
	v_min_u32_e32 v7, 56, v0
	v_mov_b32_e32 v0, s3
	ds_read_b64 v[2:3], v0
	v_lshlrev_b32_e32 v0, 3, v101
	s_movk_i32 s72, 0xf000
	v_and_or_b32 v45, v0, s72, v154
	v_lshl_or_b32 v0, v7, 6, v45
	v_ashrrev_i32_e32 v1, 31, v0
	v_and_b32_e32 v6, 0x1c0, v101
	v_lshlrev_b64 v[0:1], 10, v[0:1]
	v_and_b32_e32 v100, 56, v158
	s_waitcnt lgkmcnt(0)
	v_readfirstlane_b32 s98, v2
	v_readfirstlane_b32 s99, v3
	v_add_co_u32_e32 v4, vcc, v2, v0
	v_addc_co_u32_e32 v5, vcc, v3, v1, vcc
	v_lshlrev_b32_e32 v0, 1, v6
	v_mov_b32_e32 v1, 0
	v_add_co_u32_e32 v4, vcc, v4, v0
	v_addc_co_u32_e32 v5, vcc, v5, v1, vcc
	v_lshlrev_b32_e32 v36, 1, v100
	v_mov_b32_e32 v37, v1
	v_add_co_u32_e32 v12, vcc, v4, v36
	v_addc_co_u32_e32 v13, vcc, v5, v37, vcc
	s_mov_b32 s20, 0x8800000
	v_add_co_u32_e32 v14, vcc, s20, v12
	s_movk_i32 s73, 0xffc0
	s_nop 0
	v_addc_co_u32_e32 v15, vcc, 0, v13, vcc
	s_mov_b32 s20, 0x8808000
	v_and_or_b32 v4, v101, s73, v135
	v_add_co_u32_e32 v16, vcc, s20, v12
	v_ashrrev_i32_e32 v5, 31, v4
	s_nop 0
	v_addc_co_u32_e32 v17, vcc, 0, v13, vcc
	s_mov_b32 s20, 0x8810000
	v_lshlrev_b64 v[4:5], 13, v[4:5]
	v_add_co_u32_e32 v20, vcc, s20, v12
	v_lshl_add_u64 v[4:5], v[2:3], 0, v[4:5]
	v_lshlrev_b32_e32 v6, 7, v7
	v_mov_b32_e32 v7, v1
	v_addc_co_u32_e32 v21, vcc, 0, v13, vcc
	s_mov_b32 s20, 0x8818000
	v_add_co_u32_e32 v4, vcc, v4, v6
	v_addc_co_u32_e32 v5, vcc, v5, v7, vcc
	v_lshlrev_b32_e32 v102, 1, v134
	v_mov_b32_e32 v103, v1
	v_add_co_u32_e32 v22, vcc, s20, v12
	v_lshl_add_u64 v[28:29], v[4:5], 0, v[102:103]
	s_nop 0
	v_addc_co_u32_e32 v23, vcc, 0, v13, vcc
	s_mov_b32 s20, 0xa800000
	v_add_co_u32_e32 v30, vcc, s20, v28
	s_mov_b32 s20, 0xa820000
	s_nop 0
	v_addc_co_u32_e32 v31, vcc, 0, v29, vcc
	v_add_co_u32_e32 v32, vcc, s20, v28
	s_mov_b32 s20, 0xa840000
	s_nop 0
	v_addc_co_u32_e32 v33, vcc, 0, v29, vcc
	v_add_co_u32_e32 v38, vcc, s20, v28
	s_mov_b32 s20, 0xa860000
	s_nop 0
	v_addc_co_u32_e32 v39, vcc, 0, v29, vcc
	v_add_co_u32_e32 v40, vcc, s20, v28
	flat_load_dwordx4 v[4:7], v[14:15]
	flat_load_dwordx4 v[8:11], v[16:17]
	s_nop 0
	flat_load_dwordx4 v[12:15], v[20:21]
	flat_load_dwordx4 v[16:19], v[22:23]
	s_nop 0
	flat_load_dwordx4 v[20:23], v[30:31]
	flat_load_dwordx4 v[24:27], v[32:33]
	v_addc_co_u32_e32 v41, vcc, 0, v29, vcc
	flat_load_dwordx4 v[28:31], v[38:39]
	flat_load_dwordx4 v[32:35], v[40:41]
	v_lshl_or_b32 v38, v44, 6, v45
	v_ashrrev_i32_e32 v39, 31, v38
	v_lshlrev_b64 v[38:39], 10, v[38:39]
	v_add_co_u32_e32 v2, vcc, v2, v38
	v_addc_co_u32_e32 v3, vcc, v3, v39, vcc
	v_add_co_u32_e32 v2, vcc, v2, v0
	v_addc_co_u32_e32 v3, vcc, v3, v1, vcc
	v_add_co_u32_e32 v2, vcc, v2, v36
	v_addc_co_u32_e32 v3, vcc, v3, v37, vcc
	s_mov_b32 s74, 0x6800000
	v_add_co_u32_e32 v38, vcc, s74, v2
	s_mov_b32 s20, 0x6808000
	s_nop 0
	v_addc_co_u32_e32 v39, vcc, 0, v3, vcc
	v_add_co_u32_e32 v2, vcc, s20, v2
	v_add_u32_e32 v37, 19, v43
	s_nop 0
	v_addc_co_u32_e32 v3, vcc, 0, v3, vcc
	flat_load_dwordx4 v[44:47], v[38:39]
	flat_load_dwordx4 v[48:51], v[2:3]
	v_mul_u32_u24_e32 v38, 0x48, v154
	v_lshlrev_b32_e32 v38, 1, v38
	v_add3_u32 v124, v161, v38, v36
	v_mul_u32_u24_e32 v38, 0x90, v163
	v_lshlrev_b32_e32 v39, 1, v157
	v_add3_u32 v125, v161, v38, v39
	v_mbcnt_lo_u32_b32 v38, -1, 0
	v_mbcnt_hi_u32_b32 v38, -1, v38
	v_and_b32_e32 v40, 64, v38
	v_xor_b32_e32 v39, 16, v38
	v_add_u32_e32 v40, 64, v40
	v_add_u32_e32 v2, 17, v43
	v_add_u32_e32 v3, 18, v43
	v_cmp_lt_i32_e32 vcc, v39, v40
	v_max_i32_e32 v0, -15, v57
	v_cmp_lt_u32_e64 s[20:21], v2, v42
	v_cmp_ge_u32_e64 s[22:23], v2, v52
	v_sub_u32_e32 v2, v2, v163
	v_cmp_lt_u32_e64 s[24:25], v3, v42
	v_cmp_ge_u32_e64 s[26:27], v3, v52
	v_sub_u32_e32 v3, v3, v163
	v_cmp_lt_u32_e64 s[28:29], v37, v42
	v_cmp_ge_u32_e64 s[30:31], v37, v52
	v_sub_u32_e32 v37, v37, v163
	v_cndmask_b32_e32 v39, v38, v39, vcc
	v_add_u32_e32 v0, 15, v0
	v_max_i32_e32 v2, -15, v2
	v_max_i32_e32 v3, -15, v3
	v_max_i32_e32 v37, -15, v37
	v_lshlrev_b32_e32 v126, 2, v39
	v_xor_b32_e32 v39, 32, v38
	v_min_u32_e32 v0, 30, v0
	v_add_u32_e32 v2, 15, v2
	v_add_u32_e32 v3, 15, v3
	v_add_u32_e32 v37, 15, v37
	v_cmp_lt_i32_e32 vcc, v39, v40
	v_min_u32_e32 v2, 30, v2
	v_min_u32_e32 v3, 30, v3
	v_min_u32_e32 v37, 30, v37
	v_sub_u32_e32 v36, v155, v157
	v_cndmask_b32_e32 v38, v38, v39, vcc
	v_lshl_add_u32 v141, v0, 2, v161
	v_add3_u32 v0, v160, v156, 0
	v_cmp_ge_u32_e64 s[0:1], v43, v42
	v_cmp_lt_u32_e64 s[36:37], v43, v42
	v_cmp_ge_u32_e64 s[4:5], v43, v52
	s_mov_b32 s39, 0
	s_movk_i32 s75, 0x90
	v_lshlrev_b32_e32 v127, 2, v38
	v_or_b32_e32 v128, 64, v105
	v_mul_u32_u24_e32 v134, 0x90, v129
	v_lshl_add_u32 v136, v164, 1, v36
	v_lshl_add_u32 v137, v53, 2, v161
	v_lshl_add_u32 v138, v54, 2, v161
	v_lshl_add_u32 v139, v55, 2, v161
	v_lshl_add_u32 v140, v56, 2, v161
	v_lshl_add_u32 v142, v2, 2, v161
	v_lshl_add_u32 v143, v3, 2, v161
	v_lshl_add_u32 v144, v37, 2, v161
	v_add_u32_e32 v145, 0xb000, v0
	v_or_b32_e32 v146, 0xffffff00, v133
	s_add_i32 s76, 0, 0x24040
	s_mov_b64 s[42:43], 0x400
	s_movk_i32 s77, 0xd0
	s_mov_b64 s[44:45], 0x1c800000
	s_mov_b64 s[46:47], 0x1ca00000
	s_mov_b64 s[48:49], 0x8800000
	s_mov_b64 s[50:51], 0xa800000
	s_mov_b32 s78, 0x8000
	s_mov_b32 s79, 0x10000
	s_mov_b32 s80, 0xf149f2ca
	s_mov_b32 s81, 0xefa18f08
	s_mov_b64 s[52:53], 0x6800000
	v_mov_b32_e32 v147, 0xf149f2ca
	s_mov_b32 s82, 0
	s_branch .LBB0_408

.LBB0_414:
	s_cmp_eq_u32 s83, 5
	s_mov_b64 s[56:57], -1
	s_waitcnt lgkmcnt(0)
	s_barrier
	s_cbranch_scc1 .LBB0_420
	v_mov_b32_e32 v0, s3
	v_mov_b32_e32 v68, s98
	v_mov_b32_e32 v69, s99
	s_lshl_b32 s58, s83, 7
	s_cmp_gt_u32 s83, 2
	s_cbranch_scc0 .LBB0_417
	s_add_i32 s38, s58, 0xfffffe80
	v_add_u32_e32 v2, s38, v149
	v_ashrrev_i32_e32 v3, 31, v2
	v_lshlrev_b64 v[2:3], 10, v[2:3]
	s_waitcnt lgkmcnt(0)
	v_add_co_u32_e32 v2, vcc, v68, v2
	v_addc_co_u32_e32 v3, vcc, v69, v3, vcc
	v_add_co_u32_e32 v70, vcc, v68, v106
	v_addc_co_u32_e32 v71, vcc, v69, v107, vcc
	v_lshl_add_u64 v[2:3], v[2:3], 0, s[44:45]
	v_lshl_add_u64 v[70:71], v[70:71], 0, s[46:47]
	s_mov_b64 s[56:57], 0

.LBB0_420:
	s_and_b64 vcc, exec, s[56:57]
	s_cbranch_vccz .LBB0_451
	s_andn2_b64 vcc, exec, s[54:55]
	s_cbranch_vccnz .LBB0_423
	v_mov_b32_e32 v0, s3
	v_mov_b32_e32 v2, s98
	v_mov_b32_e32 v3, s99
	v_mov_b32_e32 v121, v1
	v_lshlrev_b32_e32 v0, 1, v100
	v_mov_b32_e32 v123, v1
	v_mov_b32_e32 v103, v1
	s_waitcnt lgkmcnt(0)
	v_add_co_u32_e32 v4, vcc, v2, v110
	v_addc_co_u32_e32 v5, vcc, v3, v111, vcc
	v_add_co_u32_e32 v6, vcc, v2, v112
	v_addc_co_u32_e32 v7, vcc, v3, v113, vcc
	v_add_co_u32_e32 v4, vcc, v4, v120
	v_addc_co_u32_e32 v5, vcc, v5, v121, vcc
	v_add_co_u32_e32 v12, vcc, v4, v0
	v_addc_co_u32_e32 v13, vcc, v5, v1, vcc
	v_add_co_u32_e32 v4, vcc, v6, v122
	v_addc_co_u32_e32 v5, vcc, v7, v123, vcc
	v_add_co_u32_e32 v28, vcc, v4, v102
	v_addc_co_u32_e32 v29, vcc, v5, v103, vcc
	v_add_co_u32_e32 v4, vcc, 0x8800000, v12
	v_lshl_add_u64 v[2:3], v[2:3], 0, v[114:115]
	s_nop 0
	v_addc_co_u32_e32 v5, vcc, 0, v13, vcc
	v_add_co_u32_e32 v8, vcc, 0x8808000, v12
	v_lshl_add_u64 v[2:3], v[2:3], 0, v[120:121]
	s_nop 0
	v_addc_co_u32_e32 v9, vcc, 0, v13, vcc
	v_add_co_u32_e32 v14, vcc, 0x8810000, v12
	v_lshl_add_u64 v[2:3], v[2:3], 0, v[0:1]
	s_nop 0
	v_addc_co_u32_e32 v15, vcc, 0, v13, vcc
	v_add_co_u32_e32 v16, vcc, 0x8818000, v12
	global_load_dwordx4 v[4:7], v[4:5], off
	s_nop 0
	global_load_dwordx4 v[8:11], v[8:9], off
	v_addc_co_u32_e32 v17, vcc, 0, v13, vcc
	v_add_co_u32_e32 v20, vcc, 0xa800000, v28
	global_load_dwordx4 v[12:15], v[14:15], off
	s_nop 0
	global_load_dwordx4 v[16:19], v[16:17], off
	v_addc_co_u32_e32 v21, vcc, 0, v29, vcc
	v_add_co_u32_e32 v24, vcc, 0xa820000, v28
	s_nop 1
	v_addc_co_u32_e32 v25, vcc, 0, v29, vcc
	v_add_co_u32_e32 v30, vcc, 0xa840000, v28
	global_load_dwordx4 v[20:23], v[20:21], off
	s_nop 0
	global_load_dwordx4 v[24:27], v[24:25], off
	v_addc_co_u32_e32 v31, vcc, 0, v29, vcc
	v_add_co_u32_e32 v32, vcc, 0xa860000, v28
	s_nop 1
	v_addc_co_u32_e32 v33, vcc, 0, v29, vcc
	v_add_co_u32_e32 v44, vcc, 0x6800000, v2
	global_load_dwordx4 v[28:31], v[30:31], off
	s_nop 0
	global_load_dwordx4 v[32:35], v[32:33], off
	v_addc_co_u32_e32 v45, vcc, 0, v3, vcc
	v_add_co_u32_e32 v2, vcc, 0x6808000, v2
	s_nop 1
	v_addc_co_u32_e32 v3, vcc, 0, v3, vcc
	global_load_dwordx4 v[44:47], v[44:45], off
	s_nop 0
	global_load_dwordx4 v[48:51], v[2:3], off
